# v23 + weight-conversion tiles: 15 redundant vmcnt(0) per call removed (second tile's 16 loads now in flight together) + prologue rebalance: adaLN workgroups no longer take conversion tiles
# speedup vs baseline: 1.0230x; 1.0125x over previous
.LBB0_211:
	s_or_b64 exec, exec, s[22:23]
	s_and_saveexec_b64 s[22:23], s[20:21]
	s_cbranch_execz .LBB0_213
	v_or_b32_e32 v21, 4, v20
	v_mad_i64_i32 v[24:25], s[28:29], v47, v21, 0
	v_lshl_add_u64 v[24:25], v[24:25], 2, v[6:7]
	global_load_dword v57, v[24:25], off
.LBB0_213:
	s_or_b64 exec, exec, s[22:23]
	v_mov_b32_e32 v55, 0
	v_mov_b32_e32 v56, 0
	s_and_saveexec_b64 s[22:23], s[20:21]
	s_cbranch_execz .LBB0_215
	v_or_b32_e32 v21, 8, v20
	v_mad_i64_i32 v[24:25], s[28:29], v47, v21, 0
	v_lshl_add_u64 v[24:25], v[24:25], 2, v[6:7]
	global_load_dword v56, v[24:25], off
.LBB0_215:
	s_or_b64 exec, exec, s[22:23]
	s_and_saveexec_b64 s[22:23], s[20:21]
	s_cbranch_execz .LBB0_217
	v_or_b32_e32 v21, 12, v20
	v_mad_i64_i32 v[24:25], s[28:29], v47, v21, 0
	v_lshl_add_u64 v[24:25], v[24:25], 2, v[6:7]
	global_load_dword v55, v[24:25], off
.LBB0_217:
	s_or_b64 exec, exec, s[22:23]
	v_mov_b32_e32 v53, 0
	v_mov_b32_e32 v54, 0
	s_and_saveexec_b64 s[22:23], s[20:21]
	s_cbranch_execz .LBB0_219
	v_or_b32_e32 v21, 16, v20
	v_mad_i64_i32 v[24:25], s[28:29], v47, v21, 0
	v_lshl_add_u64 v[24:25], v[24:25], 2, v[6:7]
	global_load_dword v54, v[24:25], off
.LBB0_219:
	s_or_b64 exec, exec, s[22:23]
	s_and_saveexec_b64 s[22:23], s[20:21]
	s_cbranch_execz .LBB0_221
	v_or_b32_e32 v21, 20, v20
	v_mad_i64_i32 v[24:25], s[28:29], v47, v21, 0
	v_lshl_add_u64 v[24:25], v[24:25], 2, v[6:7]
	global_load_dword v53, v[24:25], off
.LBB0_221:
	s_or_b64 exec, exec, s[22:23]
	v_mov_b32_e32 v51, 0
	v_mov_b32_e32 v52, 0
	s_and_saveexec_b64 s[22:23], s[20:21]
	s_cbranch_execz .LBB0_223
	v_or_b32_e32 v21, 24, v20
	v_mad_i64_i32 v[24:25], s[28:29], v47, v21, 0
	v_lshl_add_u64 v[24:25], v[24:25], 2, v[6:7]
	global_load_dword v52, v[24:25], off
.LBB0_223:
	s_or_b64 exec, exec, s[22:23]
	s_and_saveexec_b64 s[22:23], s[20:21]
	s_cbranch_execz .LBB0_225
	v_or_b32_e32 v21, 28, v20
	v_mad_i64_i32 v[24:25], s[28:29], v47, v21, 0
	v_lshl_add_u64 v[24:25], v[24:25], 2, v[6:7]
	global_load_dword v51, v[24:25], off
.LBB0_225:
	s_or_b64 exec, exec, s[22:23]
	v_mov_b32_e32 v49, 0
	v_mov_b32_e32 v50, 0
	s_and_saveexec_b64 s[22:23], s[20:21]
	s_cbranch_execz .LBB0_227
	v_or_b32_e32 v21, 32, v20
	v_mad_i64_i32 v[24:25], s[28:29], v47, v21, 0
	v_lshl_add_u64 v[24:25], v[24:25], 2, v[6:7]
	global_load_dword v50, v[24:25], off
.LBB0_227:
	s_or_b64 exec, exec, s[22:23]
	s_and_saveexec_b64 s[22:23], s[20:21]
	s_cbranch_execz .LBB0_229
	v_or_b32_e32 v21, 36, v20
	v_mad_i64_i32 v[24:25], s[28:29], v47, v21, 0
	v_lshl_add_u64 v[24:25], v[24:25], 2, v[6:7]
	global_load_dword v49, v[24:25], off
.LBB0_229:
	s_or_b64 exec, exec, s[22:23]
	v_mov_b32_e32 v46, 0
	v_mov_b32_e32 v48, 0
	s_and_saveexec_b64 s[22:23], s[20:21]
	s_cbranch_execz .LBB0_231
	v_or_b32_e32 v21, 40, v20
	v_mad_i64_i32 v[24:25], s[28:29], v47, v21, 0
	v_lshl_add_u64 v[24:25], v[24:25], 2, v[6:7]
	global_load_dword v48, v[24:25], off
.LBB0_231:
	s_or_b64 exec, exec, s[22:23]
	s_and_saveexec_b64 s[22:23], s[20:21]
	s_cbranch_execz .LBB0_233
	v_or_b32_e32 v21, 44, v20
	v_mad_i64_i32 v[24:25], s[28:29], v47, v21, 0
	v_lshl_add_u64 v[24:25], v[24:25], 2, v[6:7]
	global_load_dword v46, v[24:25], off
.LBB0_233:
	s_or_b64 exec, exec, s[22:23]
	v_mov_b32_e32 v43, 0
	v_mov_b32_e32 v45, 0
	s_and_saveexec_b64 s[22:23], s[20:21]
	s_cbranch_execz .LBB0_235
	v_or_b32_e32 v21, 48, v20
	v_mad_i64_i32 v[24:25], s[28:29], v47, v21, 0
	v_lshl_add_u64 v[24:25], v[24:25], 2, v[6:7]
	global_load_dword v45, v[24:25], off
.LBB0_235:
	s_or_b64 exec, exec, s[22:23]
	s_and_saveexec_b64 s[22:23], s[20:21]
	s_cbranch_execz .LBB0_237
	v_or_b32_e32 v21, 52, v20
	v_mad_i64_i32 v[24:25], s[28:29], v47, v21, 0
	v_lshl_add_u64 v[24:25], v[24:25], 2, v[6:7]
	global_load_dword v43, v[24:25], off

.LBB0_279:
	v_or_b32_e32 v21, 56, v20
	v_mad_i64_i32 v[58:59], s[28:29], v47, v21, 0
	v_lshl_add_u64 v[58:59], v[58:59], 2, v[6:7]
	global_load_dword v25, v[58:59], off
	s_or_b64 exec, exec, s[22:23]
	s_and_saveexec_b64 s[22:23], s[20:21]
	s_cbranch_execz .LBB0_239
.LBB0_280:
	v_or_b32_e32 v21, 60, v20
	v_mad_i64_i32 v[58:59], s[20:21], v47, v21, 0
	v_lshl_add_u64 v[6:7], v[58:59], 2, v[6:7]
	global_load_dword v24, v[6:7], off
	s_or_b64 exec, exec, s[22:23]
	v_cmp_ne_u64_e32 vcc, 0, v[10:11]
	s_and_saveexec_b64 s[20:21], vcc
	s_cbranch_execnz .LBB0_240
	s_branch .LBB0_241

.LBB0_810:
	v_readlane_b32 s48, v253, 0
	s_sub_i32 s48, s48, 48
	s_cmp_lt_i32 s48, 0
	s_cbranch_scc1 .LBB0_811
	v_readlane_b32 s4, v254, 29
	s_cmp_ge_i32 s48, s4
	s_cbranch_scc0 .LBB0_813

.LBB0_812:
	s_or_b64 exec, exec, s[20:21]
	s_add_i32 s48, s48, s50
	s_sub_i32 s48, s48, 48
	v_readlane_b32 s4, v254, 29
	s_cmp_ge_i32 s48, s4
	s_barrier
	s_cbranch_scc1 .LBB0_811

.LBB0_883:
	s_or_b64 exec, exec, s[22:23]
	s_and_saveexec_b64 s[22:23], s[20:21]
	s_cbranch_execz .LBB0_885
	v_or_b32_e32 v21, 4, v20
	v_mad_i64_i32 v[24:25], s[26:27], v47, v21, 0
	v_lshl_add_u64 v[24:25], v[24:25], 2, v[6:7]
	global_load_dword v57, v[24:25], off
.LBB0_885:
	s_or_b64 exec, exec, s[22:23]
	v_mov_b32_e32 v55, 0
	v_mov_b32_e32 v56, 0
	s_and_saveexec_b64 s[22:23], s[20:21]
	s_cbranch_execz .LBB0_887
	v_or_b32_e32 v21, 8, v20
	v_mad_i64_i32 v[24:25], s[26:27], v47, v21, 0
	v_lshl_add_u64 v[24:25], v[24:25], 2, v[6:7]
	global_load_dword v56, v[24:25], off
.LBB0_887:
	s_or_b64 exec, exec, s[22:23]
	s_and_saveexec_b64 s[22:23], s[20:21]
	s_cbranch_execz .LBB0_889
	v_or_b32_e32 v21, 12, v20
	v_mad_i64_i32 v[24:25], s[26:27], v47, v21, 0
	v_lshl_add_u64 v[24:25], v[24:25], 2, v[6:7]
	global_load_dword v55, v[24:25], off
.LBB0_889:
	s_or_b64 exec, exec, s[22:23]
	v_mov_b32_e32 v53, 0
	v_mov_b32_e32 v54, 0
	s_and_saveexec_b64 s[22:23], s[20:21]
	s_cbranch_execz .LBB0_891
	v_or_b32_e32 v21, 16, v20
	v_mad_i64_i32 v[24:25], s[26:27], v47, v21, 0
	v_lshl_add_u64 v[24:25], v[24:25], 2, v[6:7]
	global_load_dword v54, v[24:25], off
.LBB0_891:
	s_or_b64 exec, exec, s[22:23]
	s_and_saveexec_b64 s[22:23], s[20:21]
	s_cbranch_execz .LBB0_893
	v_or_b32_e32 v21, 20, v20
	v_mad_i64_i32 v[24:25], s[26:27], v47, v21, 0
	v_lshl_add_u64 v[24:25], v[24:25], 2, v[6:7]
	global_load_dword v53, v[24:25], off
.LBB0_893:
	s_or_b64 exec, exec, s[22:23]
	v_mov_b32_e32 v51, 0
	v_mov_b32_e32 v52, 0
	s_and_saveexec_b64 s[22:23], s[20:21]
	s_cbranch_execz .LBB0_895
	v_or_b32_e32 v21, 24, v20
	v_mad_i64_i32 v[24:25], s[26:27], v47, v21, 0
	v_lshl_add_u64 v[24:25], v[24:25], 2, v[6:7]
	global_load_dword v52, v[24:25], off
.LBB0_895:
	s_or_b64 exec, exec, s[22:23]
	s_and_saveexec_b64 s[22:23], s[20:21]
	s_cbranch_execz .LBB0_897
	v_or_b32_e32 v21, 28, v20
	v_mad_i64_i32 v[24:25], s[26:27], v47, v21, 0
	v_lshl_add_u64 v[24:25], v[24:25], 2, v[6:7]
	global_load_dword v51, v[24:25], off
.LBB0_897:
	s_or_b64 exec, exec, s[22:23]
	v_mov_b32_e32 v49, 0
	v_mov_b32_e32 v50, 0
	s_and_saveexec_b64 s[22:23], s[20:21]
	s_cbranch_execz .LBB0_899
	v_or_b32_e32 v21, 32, v20
	v_mad_i64_i32 v[24:25], s[26:27], v47, v21, 0
	v_lshl_add_u64 v[24:25], v[24:25], 2, v[6:7]
	global_load_dword v50, v[24:25], off
.LBB0_899:
	s_or_b64 exec, exec, s[22:23]
	s_and_saveexec_b64 s[22:23], s[20:21]
	s_cbranch_execz .LBB0_901
	v_or_b32_e32 v21, 36, v20
	v_mad_i64_i32 v[24:25], s[26:27], v47, v21, 0
	v_lshl_add_u64 v[24:25], v[24:25], 2, v[6:7]
	global_load_dword v49, v[24:25], off
.LBB0_901:
	s_or_b64 exec, exec, s[22:23]
	v_mov_b32_e32 v46, 0
	v_mov_b32_e32 v48, 0
	s_and_saveexec_b64 s[22:23], s[20:21]
	s_cbranch_execz .LBB0_903
	v_or_b32_e32 v21, 40, v20
	v_mad_i64_i32 v[24:25], s[26:27], v47, v21, 0
	v_lshl_add_u64 v[24:25], v[24:25], 2, v[6:7]
	global_load_dword v48, v[24:25], off
.LBB0_903:
	s_or_b64 exec, exec, s[22:23]
	s_and_saveexec_b64 s[22:23], s[20:21]
	s_cbranch_execz .LBB0_905
	v_or_b32_e32 v21, 44, v20
	v_mad_i64_i32 v[24:25], s[26:27], v47, v21, 0
	v_lshl_add_u64 v[24:25], v[24:25], 2, v[6:7]
	global_load_dword v46, v[24:25], off
.LBB0_905:
	s_or_b64 exec, exec, s[22:23]
	v_mov_b32_e32 v43, 0
	v_mov_b32_e32 v45, 0
	s_and_saveexec_b64 s[22:23], s[20:21]
	s_cbranch_execz .LBB0_907
	v_or_b32_e32 v21, 48, v20
	v_mad_i64_i32 v[24:25], s[26:27], v47, v21, 0
	v_lshl_add_u64 v[24:25], v[24:25], 2, v[6:7]
	global_load_dword v45, v[24:25], off
.LBB0_907:
	s_or_b64 exec, exec, s[22:23]
	s_and_saveexec_b64 s[22:23], s[20:21]
	s_cbranch_execz .LBB0_909
	v_or_b32_e32 v21, 52, v20
	v_mad_i64_i32 v[24:25], s[26:27], v47, v21, 0
	v_lshl_add_u64 v[24:25], v[24:25], 2, v[6:7]
	global_load_dword v43, v[24:25], off

.LBB0_951:
	v_or_b32_e32 v21, 56, v20
	v_mad_i64_i32 v[58:59], s[26:27], v47, v21, 0
	v_lshl_add_u64 v[58:59], v[58:59], 2, v[6:7]
	global_load_dword v25, v[58:59], off
	s_or_b64 exec, exec, s[22:23]
	s_and_saveexec_b64 s[22:23], s[20:21]
	s_cbranch_execz .LBB0_911
